# scan loop: packed horizontal add replaced by a plain v_add (cheaper issue, same value)
# baseline (speedup 1.0000x reference)
; #define LAS __attribute__((address_space(3)))
; #define SC_LD(S, X) do { const LAS float* q_ = sb + (S) * STEPF; X##kk = *(const LAS f32x4*)(q_ + lo_own); X##wr = *(const LAS f32x4*)(q_ + lo_oth); X##w = *(const LAS f32x4*)(q_ + 128 + 4 * cgp); \
;         X##k = *(const LAS f32x4*)(q_ + 192 + 4 * cgp); X##b = *(const LAS f32x4*)(q_ + 256 + 4 * cgp); X##vk = *(const LAS f32x2*)(q_ + 320 + 2 * row); } while (0)
; __device__ __forceinline__ void scan_phase(const Ctx& F, const float* sbg) {
;     ...
;             for (int ch = 0; ch < NCH; ++ch) {
;                 const LAS float* sb = bufs + (ch & 1) * (T * STEPF); LAS float* yb = ybufs + (ch & 1) * (T * 16) + rl;
;                 f32x4 Akk, Awr, Aw, Ak, Ab, Bkk, Bwr, Bw, Bk, Bb; f32x2 Avk, Bvk;
;     ...
;                 SC_LD(0, A);
; #pragma unroll
;                 for (int s = 0; s < T; s += 2) { SC_LD(s + 1, B); SC_ST(s, A); if (s + 2 < T) SC_LD(s + 2, A); SC_ST(s + 1, B); }
;     ...
;                 asm volatile("s_waitcnt lgkmcnt(0)\n\ts_barrier" ::: "memory");
.LBB0_694:
.Lscan_chunk:
	s_and_b32 s0, s22, 1
	s_mul_i32 s1, s0, 0xe000
	v_lshl_add_u32 v86, v171, 2, s1
	v_lshl_add_u32 v84, v173, 2, s1
	v_lshl_add_u32 v83, v1, 2, s1
	v_lshl_add_u32 v85, v82, 2, s1
	v_lshl_add_u32 v94, s0, 11, v206
	ds_read_b128 v[18:21], v86 offset:0
	ds_read_b128 v[22:25], v84 offset:0
	ds_read_b128 v[26:29], v83 offset:512
	ds_read_b128 v[30:33], v83 offset:768
	ds_read_b128 v[34:37], v83 offset:1024
	ds_read_b64 v[38:39], v85 offset:1280
	v_add_u32_e32 v94, v94, v198
	ds_read_b128 v[40:43], v86 offset:1792
	ds_read_b128 v[44:47], v84 offset:1792
	ds_read_b128 v[48:51], v83 offset:2304
	ds_read_b128 v[52:55], v83 offset:2560
	ds_read_b128 v[56:59], v83 offset:2816
	ds_read_b64 v[60:61], v85 offset:3072
	s_waitcnt lgkmcnt(6)
	v_pk_mul_f32 v[4:5], v[18:19], v[16:17]
	v_pk_mul_f32 v[6:7], v[22:23], v[16:17]
	v_pk_fma_f32 v[4:5], v[20:21], v[78:79], v[4:5]
	v_pk_fma_f32 v[6:7], v[24:25], v[78:79], v[6:7]
	v_add_f32_e32 v2, v4, v5
	v_add_f32_e32 v8, v6, v7
	v_pk_mul_f32 v[14:15], v[26:27], v[16:17]
	v_pk_mul_f32 v[62:63], v[28:29], v[78:79]
	v_add_f32_dpp v10, v8, v2 quad_perm:[1,0,3,2] row_mask:0xf bank_mask:0xf bound_ctrl:1
	v_pk_fma_f32 v[14:15], v[30:31], v[38:39], v[14:15] op_sel_hi:[1,0,1]
	v_pk_fma_f32 v[62:63], v[32:33], v[38:39], v[62:63] op_sel_hi:[1,0,1]
	v_add_f32_dpp v10, v10, v10 quad_perm:[2,3,0,1] row_mask:0xf bank_mask:0xf bound_ctrl:1
	ds_read_b128 v[100:103], v86 offset:3584
	ds_read_b128 v[104:107], v84 offset:3584
	v_add_f32_dpp v10, v10, v10 row_ror:4 row_mask:0xf bank_mask:0xf bound_ctrl:1
	ds_read_b128 v[108:111], v83 offset:4096
	ds_read_b128 v[112:115], v83 offset:4352
	v_add_f32_dpp v11, v10, v10 row_ror:8 row_mask:0xf bank_mask:0xf bound_ctrl:1
	ds_read_b128 v[116:119], v83 offset:4608
	ds_read_b64 v[120:121], v85 offset:4864
	v_mov_b32_dpp v12, v11 quad_perm:[0,0,2,2] row_mask:0xf bank_mask:0xf bound_ctrl:1
	v_pk_fma_f32 v[16:17], v[34:35], v[12:13], v[14:15] op_sel_hi:[1,0,1] neg_lo:[1,0,0] neg_hi:[1,0,0]
	v_pk_fma_f32 v[78:79], v[36:37], v[12:13], v[62:63] op_sel_hi:[1,0,1] neg_lo:[1,0,0] neg_hi:[1,0,0]
	v_fmac_f32_e32 v11, v38, v39
	v_cndmask_b32_e64 v87, v87, v11, s[4:5]
	s_waitcnt lgkmcnt(6)
	v_pk_mul_f32 v[4:5], v[40:41], v[16:17]
	v_pk_mul_f32 v[6:7], v[44:45], v[16:17]
	v_pk_fma_f32 v[4:5], v[42:43], v[78:79], v[4:5]
	v_pk_fma_f32 v[6:7], v[46:47], v[78:79], v[6:7]
	v_add_f32_e32 v2, v4, v5
	v_add_f32_e32 v8, v6, v7
	v_pk_mul_f32 v[14:15], v[48:49], v[16:17]
	v_pk_mul_f32 v[62:63], v[50:51], v[78:79]
	v_add_f32_dpp v10, v8, v2 quad_perm:[1,0,3,2] row_mask:0xf bank_mask:0xf bound_ctrl:1
	v_pk_fma_f32 v[14:15], v[52:53], v[60:61], v[14:15] op_sel_hi:[1,0,1]
	v_pk_fma_f32 v[62:63], v[54:55], v[60:61], v[62:63] op_sel_hi:[1,0,1]
	v_add_f32_dpp v10, v10, v10 quad_perm:[2,3,0,1] row_mask:0xf bank_mask:0xf bound_ctrl:1
	ds_read_b128 v[122:125], v86 offset:5376
	ds_read_b128 v[126:129], v84 offset:5376
	v_add_f32_dpp v10, v10, v10 row_ror:4 row_mask:0xf bank_mask:0xf bound_ctrl:1
	ds_read_b128 v[130:133], v83 offset:5888
	ds_read_b128 v[134:137], v83 offset:6144
	v_add_f32_dpp v11, v10, v10 row_ror:8 row_mask:0xf bank_mask:0xf bound_ctrl:1
	ds_read_b128 v[138:141], v83 offset:6400
	ds_read_b64 v[142:143], v85 offset:6656
	v_mov_b32_dpp v12, v11 quad_perm:[0,0,2,2] row_mask:0xf bank_mask:0xf bound_ctrl:1
	v_pk_fma_f32 v[16:17], v[56:57], v[12:13], v[14:15] op_sel_hi:[1,0,1] neg_lo:[1,0,0] neg_hi:[1,0,0]
	v_pk_fma_f32 v[78:79], v[58:59], v[12:13], v[62:63] op_sel_hi:[1,0,1] neg_lo:[1,0,0] neg_hi:[1,0,0]
	v_fmac_f32_e32 v11, v60, v61
	v_cndmask_b32_e64 v87, v87, v11, s[6:7]
	s_waitcnt lgkmcnt(6)
	v_pk_mul_f32 v[4:5], v[100:101], v[16:17]
	v_pk_mul_f32 v[6:7], v[104:105], v[16:17]
	v_pk_fma_f32 v[4:5], v[102:103], v[78:79], v[4:5]
	v_pk_fma_f32 v[6:7], v[106:107], v[78:79], v[6:7]
	v_add_f32_e32 v2, v4, v5
	v_add_f32_e32 v8, v6, v7
	v_pk_mul_f32 v[14:15], v[108:109], v[16:17]
	v_pk_mul_f32 v[62:63], v[110:111], v[78:79]
	v_add_f32_dpp v10, v8, v2 quad_perm:[1,0,3,2] row_mask:0xf bank_mask:0xf bound_ctrl:1
	v_pk_fma_f32 v[14:15], v[112:113], v[120:121], v[14:15] op_sel_hi:[1,0,1]
	v_pk_fma_f32 v[62:63], v[114:115], v[120:121], v[62:63] op_sel_hi:[1,0,1]
	v_add_f32_dpp v10, v10, v10 quad_perm:[2,3,0,1] row_mask:0xf bank_mask:0xf bound_ctrl:1
	ds_read_b128 v[18:21], v86 offset:7168
	ds_read_b128 v[22:25], v84 offset:7168
	v_add_f32_dpp v10, v10, v10 row_ror:4 row_mask:0xf bank_mask:0xf bound_ctrl:1
	ds_read_b128 v[26:29], v83 offset:7680
	ds_read_b128 v[30:33], v83 offset:7936
	v_add_f32_dpp v11, v10, v10 row_ror:8 row_mask:0xf bank_mask:0xf bound_ctrl:1
	ds_read_b128 v[34:37], v83 offset:8192
	ds_read_b64 v[38:39], v85 offset:8448
	v_mov_b32_dpp v12, v11 quad_perm:[0,0,2,2] row_mask:0xf bank_mask:0xf bound_ctrl:1
	v_pk_fma_f32 v[16:17], v[116:117], v[12:13], v[14:15] op_sel_hi:[1,0,1] neg_lo:[1,0,0] neg_hi:[1,0,0]
	v_pk_fma_f32 v[78:79], v[118:119], v[12:13], v[62:63] op_sel_hi:[1,0,1] neg_lo:[1,0,0] neg_hi:[1,0,0]
	v_fmac_f32_e32 v11, v120, v121
	v_cndmask_b32_e64 v87, v87, v11, s[8:9]
	s_waitcnt lgkmcnt(6)
; #define SC_LD(S, X) do { const LAS float* q_ = sb + (S) * STEPF; X##kk = *(const LAS f32x4*)(q_ + lo_own); X##wr = *(const LAS f32x4*)(q_ + lo_oth); X##w = *(const LAS f32x4*)(q_ + 128 + 4 * cgp); \
;         X##k = *(const LAS f32x4*)(q_ + 192 + 4 * cgp); X##b = *(const LAS f32x4*)(q_ + 256 + 4 * cgp); X##vk = *(const LAS f32x2*)(q_ + 320 + 2 * row); } while (0)
; __device__ __forceinline__ void scan_phase(const Ctx& F, const float* sbg) {
;     ...
;                 SC_LD(0, A);
; #pragma unroll
;                 for (int s = 0; s < T; s += 2) { SC_LD(s + 1, B); SC_ST(s, A); if (s + 2 < T) SC_LD(s + 2, A); SC_ST(s + 1, B); }
	v_pk_mul_f32 v[4:5], v[122:123], v[16:17]
	v_pk_mul_f32 v[6:7], v[126:127], v[16:17]
	v_pk_fma_f32 v[4:5], v[124:125], v[78:79], v[4:5]
	v_pk_fma_f32 v[6:7], v[128:129], v[78:79], v[6:7]
	v_add_f32_e32 v2, v4, v5
	v_add_f32_e32 v8, v6, v7
	v_pk_mul_f32 v[14:15], v[130:131], v[16:17]
	v_pk_mul_f32 v[62:63], v[132:133], v[78:79]
	v_add_f32_dpp v10, v8, v2 quad_perm:[1,0,3,2] row_mask:0xf bank_mask:0xf bound_ctrl:1
	v_pk_fma_f32 v[14:15], v[134:135], v[142:143], v[14:15] op_sel_hi:[1,0,1]
	v_pk_fma_f32 v[62:63], v[136:137], v[142:143], v[62:63] op_sel_hi:[1,0,1]
	v_add_f32_dpp v10, v10, v10 quad_perm:[2,3,0,1] row_mask:0xf bank_mask:0xf bound_ctrl:1
	ds_read_b128 v[40:43], v86 offset:8960
	ds_read_b128 v[44:47], v84 offset:8960
	v_add_f32_dpp v10, v10, v10 row_ror:4 row_mask:0xf bank_mask:0xf bound_ctrl:1
	ds_read_b128 v[48:51], v83 offset:9472
	ds_read_b128 v[52:55], v83 offset:9728
	v_add_f32_dpp v11, v10, v10 row_ror:8 row_mask:0xf bank_mask:0xf bound_ctrl:1
	ds_read_b128 v[56:59], v83 offset:9984
	ds_read_b64 v[60:61], v85 offset:10240
	v_mov_b32_dpp v12, v11 quad_perm:[0,0,2,2] row_mask:0xf bank_mask:0xf bound_ctrl:1
	v_pk_fma_f32 v[16:17], v[138:139], v[12:13], v[14:15] op_sel_hi:[1,0,1] neg_lo:[1,0,0] neg_hi:[1,0,0]
	v_pk_fma_f32 v[78:79], v[140:141], v[12:13], v[62:63] op_sel_hi:[1,0,1] neg_lo:[1,0,0] neg_hi:[1,0,0]
	v_fmac_f32_e32 v11, v142, v143
	v_cndmask_b32_e64 v87, v87, v11, s[10:11]
	s_waitcnt lgkmcnt(6)
	v_pk_mul_f32 v[4:5], v[18:19], v[16:17]
	v_pk_mul_f32 v[6:7], v[22:23], v[16:17]
	v_pk_fma_f32 v[4:5], v[20:21], v[78:79], v[4:5]
	v_pk_fma_f32 v[6:7], v[24:25], v[78:79], v[6:7]
	v_add_f32_e32 v2, v4, v5
	v_add_f32_e32 v8, v6, v7
	v_pk_mul_f32 v[14:15], v[26:27], v[16:17]
	v_pk_mul_f32 v[62:63], v[28:29], v[78:79]
	v_add_f32_dpp v10, v8, v2 quad_perm:[1,0,3,2] row_mask:0xf bank_mask:0xf bound_ctrl:1
	v_pk_fma_f32 v[14:15], v[30:31], v[38:39], v[14:15] op_sel_hi:[1,0,1]
	v_pk_fma_f32 v[62:63], v[32:33], v[38:39], v[62:63] op_sel_hi:[1,0,1]
	v_add_f32_dpp v10, v10, v10 quad_perm:[2,3,0,1] row_mask:0xf bank_mask:0xf bound_ctrl:1
	ds_read_b128 v[100:103], v86 offset:10752
	ds_read_b128 v[104:107], v84 offset:10752
	v_add_f32_dpp v10, v10, v10 row_ror:4 row_mask:0xf bank_mask:0xf bound_ctrl:1
	ds_read_b128 v[108:111], v83 offset:11264
	ds_read_b128 v[112:115], v83 offset:11520
	v_add_f32_dpp v11, v10, v10 row_ror:8 row_mask:0xf bank_mask:0xf bound_ctrl:1
	ds_read_b128 v[116:119], v83 offset:11776
	ds_read_b64 v[120:121], v85 offset:12032
	v_mov_b32_dpp v12, v11 quad_perm:[0,0,2,2] row_mask:0xf bank_mask:0xf bound_ctrl:1
	v_pk_fma_f32 v[16:17], v[34:35], v[12:13], v[14:15] op_sel_hi:[1,0,1] neg_lo:[1,0,0] neg_hi:[1,0,0]
	v_pk_fma_f32 v[78:79], v[36:37], v[12:13], v[62:63] op_sel_hi:[1,0,1] neg_lo:[1,0,0] neg_hi:[1,0,0]
	v_fmac_f32_e32 v11, v38, v39
	v_cndmask_b32_e64 v87, v87, v11, s[12:13]
	s_waitcnt lgkmcnt(6)
	v_pk_mul_f32 v[4:5], v[40:41], v[16:17]
	v_pk_mul_f32 v[6:7], v[44:45], v[16:17]
	v_pk_fma_f32 v[4:5], v[42:43], v[78:79], v[4:5]
	v_pk_fma_f32 v[6:7], v[46:47], v[78:79], v[6:7]
	v_add_f32_e32 v2, v4, v5
	v_add_f32_e32 v8, v6, v7
	v_pk_mul_f32 v[14:15], v[48:49], v[16:17]
	v_pk_mul_f32 v[62:63], v[50:51], v[78:79]
	v_add_f32_dpp v10, v8, v2 quad_perm:[1,0,3,2] row_mask:0xf bank_mask:0xf bound_ctrl:1
	v_pk_fma_f32 v[14:15], v[52:53], v[60:61], v[14:15] op_sel_hi:[1,0,1]
	v_pk_fma_f32 v[62:63], v[54:55], v[60:61], v[62:63] op_sel_hi:[1,0,1]
	v_add_f32_dpp v10, v10, v10 quad_perm:[2,3,0,1] row_mask:0xf bank_mask:0xf bound_ctrl:1
	ds_read_b128 v[122:125], v86 offset:12544
	ds_read_b128 v[126:129], v84 offset:12544
	v_add_f32_dpp v10, v10, v10 row_ror:4 row_mask:0xf bank_mask:0xf bound_ctrl:1
	ds_read_b128 v[130:133], v83 offset:13056
	ds_read_b128 v[134:137], v83 offset:13312
	v_add_f32_dpp v11, v10, v10 row_ror:8 row_mask:0xf bank_mask:0xf bound_ctrl:1
	ds_read_b128 v[138:141], v83 offset:13568
	ds_read_b64 v[142:143], v85 offset:13824
	v_mov_b32_dpp v12, v11 quad_perm:[0,0,2,2] row_mask:0xf bank_mask:0xf bound_ctrl:1
	v_pk_fma_f32 v[16:17], v[56:57], v[12:13], v[14:15] op_sel_hi:[1,0,1] neg_lo:[1,0,0] neg_hi:[1,0,0]
	v_pk_fma_f32 v[78:79], v[58:59], v[12:13], v[62:63] op_sel_hi:[1,0,1] neg_lo:[1,0,0] neg_hi:[1,0,0]
	v_fmac_f32_e32 v11, v60, v61
	v_cndmask_b32_e64 v87, v87, v11, s[14:15]
	s_waitcnt lgkmcnt(6)
	v_pk_mul_f32 v[4:5], v[100:101], v[16:17]
	v_pk_mul_f32 v[6:7], v[104:105], v[16:17]
	v_pk_fma_f32 v[4:5], v[102:103], v[78:79], v[4:5]
	v_pk_fma_f32 v[6:7], v[106:107], v[78:79], v[6:7]
	v_add_f32_e32 v2, v4, v5
	v_add_f32_e32 v8, v6, v7
	v_pk_mul_f32 v[14:15], v[108:109], v[16:17]
	v_pk_mul_f32 v[62:63], v[110:111], v[78:79]
	v_add_f32_dpp v10, v8, v2 quad_perm:[1,0,3,2] row_mask:0xf bank_mask:0xf bound_ctrl:1
	v_pk_fma_f32 v[14:15], v[112:113], v[120:121], v[14:15] op_sel_hi:[1,0,1]
	v_pk_fma_f32 v[62:63], v[114:115], v[120:121], v[62:63] op_sel_hi:[1,0,1]
	v_add_f32_dpp v10, v10, v10 quad_perm:[2,3,0,1] row_mask:0xf bank_mask:0xf bound_ctrl:1
	ds_read_b128 v[18:21], v86 offset:14336
	ds_read_b128 v[22:25], v84 offset:14336
	v_add_f32_dpp v10, v10, v10 row_ror:4 row_mask:0xf bank_mask:0xf bound_ctrl:1
	ds_read_b128 v[26:29], v83 offset:14848
	ds_read_b128 v[30:33], v83 offset:15104
	v_add_f32_dpp v11, v10, v10 row_ror:8 row_mask:0xf bank_mask:0xf bound_ctrl:1
	ds_read_b128 v[34:37], v83 offset:15360
	ds_read_b64 v[38:39], v85 offset:15616
	v_mov_b32_dpp v12, v11 quad_perm:[0,0,2,2] row_mask:0xf bank_mask:0xf bound_ctrl:1
	v_pk_fma_f32 v[16:17], v[116:117], v[12:13], v[14:15] op_sel_hi:[1,0,1] neg_lo:[1,0,0] neg_hi:[1,0,0]
	v_pk_fma_f32 v[78:79], v[118:119], v[12:13], v[62:63] op_sel_hi:[1,0,1] neg_lo:[1,0,0] neg_hi:[1,0,0]
	v_fmac_f32_e32 v11, v120, v121
	v_cndmask_b32_e64 v87, v87, v11, s[16:17]
	s_waitcnt lgkmcnt(6)
; #define SC_LD(S, X) do { const LAS float* q_ = sb + (S) * STEPF; X##kk = *(const LAS f32x4*)(q_ + lo_own); X##wr = *(const LAS f32x4*)(q_ + lo_oth); X##w = *(const LAS f32x4*)(q_ + 128 + 4 * cgp); \
;         X##k = *(const LAS f32x4*)(q_ + 192 + 4 * cgp); X##b = *(const LAS f32x4*)(q_ + 256 + 4 * cgp); X##vk = *(const LAS f32x2*)(q_ + 320 + 2 * row); } while (0)
; __device__ __forceinline__ void scan_phase(const Ctx& F, const float* sbg) {
;     ...
;                 SC_LD(0, A);
; #pragma unroll
;                 for (int s = 0; s < T; s += 2) { SC_LD(s + 1, B); SC_ST(s, A); if (s + 2 < T) SC_LD(s + 2, A); SC_ST(s + 1, B); }
	v_pk_mul_f32 v[4:5], v[122:123], v[16:17]
	v_pk_mul_f32 v[6:7], v[126:127], v[16:17]
	v_pk_fma_f32 v[4:5], v[124:125], v[78:79], v[4:5]
	v_pk_fma_f32 v[6:7], v[128:129], v[78:79], v[6:7]
	v_add_f32_e32 v2, v4, v5
	v_add_f32_e32 v8, v6, v7
	v_pk_mul_f32 v[14:15], v[130:131], v[16:17]
	v_pk_mul_f32 v[62:63], v[132:133], v[78:79]
	v_add_f32_dpp v10, v8, v2 quad_perm:[1,0,3,2] row_mask:0xf bank_mask:0xf bound_ctrl:1
	v_pk_fma_f32 v[14:15], v[134:135], v[142:143], v[14:15] op_sel_hi:[1,0,1]
	v_pk_fma_f32 v[62:63], v[136:137], v[142:143], v[62:63] op_sel_hi:[1,0,1]
	v_add_f32_dpp v10, v10, v10 quad_perm:[2,3,0,1] row_mask:0xf bank_mask:0xf bound_ctrl:1
	ds_read_b128 v[40:43], v86 offset:16128
	ds_read_b128 v[44:47], v84 offset:16128
	v_add_f32_dpp v10, v10, v10 row_ror:4 row_mask:0xf bank_mask:0xf bound_ctrl:1
	ds_read_b128 v[48:51], v83 offset:16640
	ds_read_b128 v[52:55], v83 offset:16896
	v_add_f32_dpp v11, v10, v10 row_ror:8 row_mask:0xf bank_mask:0xf bound_ctrl:1
	ds_read_b128 v[56:59], v83 offset:17152
	ds_read_b64 v[60:61], v85 offset:17408
	v_mov_b32_dpp v12, v11 quad_perm:[0,0,2,2] row_mask:0xf bank_mask:0xf bound_ctrl:1
	v_pk_fma_f32 v[16:17], v[138:139], v[12:13], v[14:15] op_sel_hi:[1,0,1] neg_lo:[1,0,0] neg_hi:[1,0,0]
	v_pk_fma_f32 v[78:79], v[140:141], v[12:13], v[62:63] op_sel_hi:[1,0,1] neg_lo:[1,0,0] neg_hi:[1,0,0]
	v_fmac_f32_e32 v11, v142, v143
	v_cndmask_b32_e64 v87, v87, v11, s[18:19]
	s_and_saveexec_b64 s[0:1], s[2:3]
	ds_write_b32 v94, v87
	s_or_b64 exec, exec, s[0:1]
	s_waitcnt lgkmcnt(6)
	v_pk_mul_f32 v[4:5], v[18:19], v[16:17]
	v_pk_mul_f32 v[6:7], v[22:23], v[16:17]
	v_pk_fma_f32 v[4:5], v[20:21], v[78:79], v[4:5]
	v_pk_fma_f32 v[6:7], v[24:25], v[78:79], v[6:7]
	v_add_f32_e32 v2, v4, v5
	v_add_f32_e32 v8, v6, v7
	v_pk_mul_f32 v[14:15], v[26:27], v[16:17]
	v_pk_mul_f32 v[62:63], v[28:29], v[78:79]
	v_add_f32_dpp v10, v8, v2 quad_perm:[1,0,3,2] row_mask:0xf bank_mask:0xf bound_ctrl:1
	v_pk_fma_f32 v[14:15], v[30:31], v[38:39], v[14:15] op_sel_hi:[1,0,1]
	v_pk_fma_f32 v[62:63], v[32:33], v[38:39], v[62:63] op_sel_hi:[1,0,1]
	v_add_f32_dpp v10, v10, v10 quad_perm:[2,3,0,1] row_mask:0xf bank_mask:0xf bound_ctrl:1
	ds_read_b128 v[100:103], v86 offset:17920
	ds_read_b128 v[104:107], v84 offset:17920
	v_add_f32_dpp v10, v10, v10 row_ror:4 row_mask:0xf bank_mask:0xf bound_ctrl:1
	ds_read_b128 v[108:111], v83 offset:18432
	ds_read_b128 v[112:115], v83 offset:18688
	v_add_f32_dpp v11, v10, v10 row_ror:8 row_mask:0xf bank_mask:0xf bound_ctrl:1
	ds_read_b128 v[116:119], v83 offset:18944
	ds_read_b64 v[120:121], v85 offset:19200
	v_mov_b32_dpp v12, v11 quad_perm:[0,0,2,2] row_mask:0xf bank_mask:0xf bound_ctrl:1
	v_pk_fma_f32 v[16:17], v[34:35], v[12:13], v[14:15] op_sel_hi:[1,0,1] neg_lo:[1,0,0] neg_hi:[1,0,0]
	v_pk_fma_f32 v[78:79], v[36:37], v[12:13], v[62:63] op_sel_hi:[1,0,1] neg_lo:[1,0,0] neg_hi:[1,0,0]
	v_fmac_f32_e32 v11, v38, v39
	v_cndmask_b32_e64 v87, v87, v11, s[4:5]
	s_waitcnt lgkmcnt(6)
	v_pk_mul_f32 v[4:5], v[40:41], v[16:17]
	v_pk_mul_f32 v[6:7], v[44:45], v[16:17]
	v_pk_fma_f32 v[4:5], v[42:43], v[78:79], v[4:5]
	v_pk_fma_f32 v[6:7], v[46:47], v[78:79], v[6:7]
	v_add_f32_e32 v2, v4, v5
	v_add_f32_e32 v8, v6, v7
	v_pk_mul_f32 v[14:15], v[48:49], v[16:17]
	v_pk_mul_f32 v[62:63], v[50:51], v[78:79]
	v_add_f32_dpp v10, v8, v2 quad_perm:[1,0,3,2] row_mask:0xf bank_mask:0xf bound_ctrl:1
	v_pk_fma_f32 v[14:15], v[52:53], v[60:61], v[14:15] op_sel_hi:[1,0,1]
	v_pk_fma_f32 v[62:63], v[54:55], v[60:61], v[62:63] op_sel_hi:[1,0,1]
	v_add_f32_dpp v10, v10, v10 quad_perm:[2,3,0,1] row_mask:0xf bank_mask:0xf bound_ctrl:1
	ds_read_b128 v[122:125], v86 offset:19712
	ds_read_b128 v[126:129], v84 offset:19712
	v_add_f32_dpp v10, v10, v10 row_ror:4 row_mask:0xf bank_mask:0xf bound_ctrl:1
	ds_read_b128 v[130:133], v83 offset:20224
	ds_read_b128 v[134:137], v83 offset:20480
	v_add_f32_dpp v11, v10, v10 row_ror:8 row_mask:0xf bank_mask:0xf bound_ctrl:1
	ds_read_b128 v[138:141], v83 offset:20736
	ds_read_b64 v[142:143], v85 offset:20992
	v_mov_b32_dpp v12, v11 quad_perm:[0,0,2,2] row_mask:0xf bank_mask:0xf bound_ctrl:1
	v_pk_fma_f32 v[16:17], v[56:57], v[12:13], v[14:15] op_sel_hi:[1,0,1] neg_lo:[1,0,0] neg_hi:[1,0,0]
	v_pk_fma_f32 v[78:79], v[58:59], v[12:13], v[62:63] op_sel_hi:[1,0,1] neg_lo:[1,0,0] neg_hi:[1,0,0]
	v_fmac_f32_e32 v11, v60, v61
	v_cndmask_b32_e64 v87, v87, v11, s[6:7]
	s_waitcnt lgkmcnt(6)
	v_pk_mul_f32 v[4:5], v[100:101], v[16:17]
	v_pk_mul_f32 v[6:7], v[104:105], v[16:17]
	v_pk_fma_f32 v[4:5], v[102:103], v[78:79], v[4:5]
	v_pk_fma_f32 v[6:7], v[106:107], v[78:79], v[6:7]
	v_add_f32_e32 v2, v4, v5
	v_add_f32_e32 v8, v6, v7
	v_pk_mul_f32 v[14:15], v[108:109], v[16:17]
	v_pk_mul_f32 v[62:63], v[110:111], v[78:79]
	v_add_f32_dpp v10, v8, v2 quad_perm:[1,0,3,2] row_mask:0xf bank_mask:0xf bound_ctrl:1
	v_pk_fma_f32 v[14:15], v[112:113], v[120:121], v[14:15] op_sel_hi:[1,0,1]
	v_pk_fma_f32 v[62:63], v[114:115], v[120:121], v[62:63] op_sel_hi:[1,0,1]
	v_add_f32_dpp v10, v10, v10 quad_perm:[2,3,0,1] row_mask:0xf bank_mask:0xf bound_ctrl:1
	ds_read_b128 v[18:21], v86 offset:21504
	ds_read_b128 v[22:25], v84 offset:21504
	v_add_f32_dpp v10, v10, v10 row_ror:4 row_mask:0xf bank_mask:0xf bound_ctrl:1
	ds_read_b128 v[26:29], v83 offset:22016
	ds_read_b128 v[30:33], v83 offset:22272
	v_add_f32_dpp v11, v10, v10 row_ror:8 row_mask:0xf bank_mask:0xf bound_ctrl:1
	ds_read_b128 v[34:37], v83 offset:22528
	ds_read_b64 v[38:39], v85 offset:22784
	v_mov_b32_dpp v12, v11 quad_perm:[0,0,2,2] row_mask:0xf bank_mask:0xf bound_ctrl:1
	v_pk_fma_f32 v[16:17], v[116:117], v[12:13], v[14:15] op_sel_hi:[1,0,1] neg_lo:[1,0,0] neg_hi:[1,0,0]
	v_pk_fma_f32 v[78:79], v[118:119], v[12:13], v[62:63] op_sel_hi:[1,0,1] neg_lo:[1,0,0] neg_hi:[1,0,0]
	v_fmac_f32_e32 v11, v120, v121
	v_cndmask_b32_e64 v87, v87, v11, s[8:9]
	s_waitcnt lgkmcnt(6)
; #define SC_LD(S, X) do { const LAS float* q_ = sb + (S) * STEPF; X##kk = *(const LAS f32x4*)(q_ + lo_own); X##wr = *(const LAS f32x4*)(q_ + lo_oth); X##w = *(const LAS f32x4*)(q_ + 128 + 4 * cgp); \
;         X##k = *(const LAS f32x4*)(q_ + 192 + 4 * cgp); X##b = *(const LAS f32x4*)(q_ + 256 + 4 * cgp); X##vk = *(const LAS f32x2*)(q_ + 320 + 2 * row); } while (0)
; __device__ __forceinline__ void scan_phase(const Ctx& F, const float* sbg) {
;     ...
;                 SC_LD(0, A);
; #pragma unroll
;                 for (int s = 0; s < T; s += 2) { SC_LD(s + 1, B); SC_ST(s, A); if (s + 2 < T) SC_LD(s + 2, A); SC_ST(s + 1, B); }
	v_pk_mul_f32 v[4:5], v[122:123], v[16:17]
	v_pk_mul_f32 v[6:7], v[126:127], v[16:17]
	v_pk_fma_f32 v[4:5], v[124:125], v[78:79], v[4:5]
	v_pk_fma_f32 v[6:7], v[128:129], v[78:79], v[6:7]
	v_add_f32_e32 v2, v4, v5
	v_add_f32_e32 v8, v6, v7
	v_pk_mul_f32 v[14:15], v[130:131], v[16:17]
	v_pk_mul_f32 v[62:63], v[132:133], v[78:79]
	v_add_f32_dpp v10, v8, v2 quad_perm:[1,0,3,2] row_mask:0xf bank_mask:0xf bound_ctrl:1
	v_pk_fma_f32 v[14:15], v[134:135], v[142:143], v[14:15] op_sel_hi:[1,0,1]
	v_pk_fma_f32 v[62:63], v[136:137], v[142:143], v[62:63] op_sel_hi:[1,0,1]
	v_add_f32_dpp v10, v10, v10 quad_perm:[2,3,0,1] row_mask:0xf bank_mask:0xf bound_ctrl:1
	ds_read_b128 v[40:43], v86 offset:23296
	ds_read_b128 v[44:47], v84 offset:23296
	v_add_f32_dpp v10, v10, v10 row_ror:4 row_mask:0xf bank_mask:0xf bound_ctrl:1
	ds_read_b128 v[48:51], v83 offset:23808
	ds_read_b128 v[52:55], v83 offset:24064
	v_add_f32_dpp v11, v10, v10 row_ror:8 row_mask:0xf bank_mask:0xf bound_ctrl:1
	ds_read_b128 v[56:59], v83 offset:24320
	ds_read_b64 v[60:61], v85 offset:24576
	v_mov_b32_dpp v12, v11 quad_perm:[0,0,2,2] row_mask:0xf bank_mask:0xf bound_ctrl:1
	v_pk_fma_f32 v[16:17], v[138:139], v[12:13], v[14:15] op_sel_hi:[1,0,1] neg_lo:[1,0,0] neg_hi:[1,0,0]
	v_pk_fma_f32 v[78:79], v[140:141], v[12:13], v[62:63] op_sel_hi:[1,0,1] neg_lo:[1,0,0] neg_hi:[1,0,0]
	v_fmac_f32_e32 v11, v142, v143
	v_cndmask_b32_e64 v87, v87, v11, s[10:11]
	s_waitcnt lgkmcnt(6)
	v_pk_mul_f32 v[4:5], v[18:19], v[16:17]
	v_pk_mul_f32 v[6:7], v[22:23], v[16:17]
	v_pk_fma_f32 v[4:5], v[20:21], v[78:79], v[4:5]
	v_pk_fma_f32 v[6:7], v[24:25], v[78:79], v[6:7]
	v_add_f32_e32 v2, v4, v5
	v_add_f32_e32 v8, v6, v7
	v_pk_mul_f32 v[14:15], v[26:27], v[16:17]
	v_pk_mul_f32 v[62:63], v[28:29], v[78:79]
	v_add_f32_dpp v10, v8, v2 quad_perm:[1,0,3,2] row_mask:0xf bank_mask:0xf bound_ctrl:1
	v_pk_fma_f32 v[14:15], v[30:31], v[38:39], v[14:15] op_sel_hi:[1,0,1]
	v_pk_fma_f32 v[62:63], v[32:33], v[38:39], v[62:63] op_sel_hi:[1,0,1]
	v_add_f32_dpp v10, v10, v10 quad_perm:[2,3,0,1] row_mask:0xf bank_mask:0xf bound_ctrl:1
	ds_read_b128 v[100:103], v86 offset:25088
	ds_read_b128 v[104:107], v84 offset:25088
	v_add_f32_dpp v10, v10, v10 row_ror:4 row_mask:0xf bank_mask:0xf bound_ctrl:1
	ds_read_b128 v[108:111], v83 offset:25600
	ds_read_b128 v[112:115], v83 offset:25856
	v_add_f32_dpp v11, v10, v10 row_ror:8 row_mask:0xf bank_mask:0xf bound_ctrl:1
	ds_read_b128 v[116:119], v83 offset:26112
	ds_read_b64 v[120:121], v85 offset:26368
	v_mov_b32_dpp v12, v11 quad_perm:[0,0,2,2] row_mask:0xf bank_mask:0xf bound_ctrl:1
	v_pk_fma_f32 v[16:17], v[34:35], v[12:13], v[14:15] op_sel_hi:[1,0,1] neg_lo:[1,0,0] neg_hi:[1,0,0]
	v_pk_fma_f32 v[78:79], v[36:37], v[12:13], v[62:63] op_sel_hi:[1,0,1] neg_lo:[1,0,0] neg_hi:[1,0,0]
	v_fmac_f32_e32 v11, v38, v39
	v_cndmask_b32_e64 v87, v87, v11, s[12:13]
	s_waitcnt lgkmcnt(6)
	v_pk_mul_f32 v[4:5], v[40:41], v[16:17]
	v_pk_mul_f32 v[6:7], v[44:45], v[16:17]
	v_pk_fma_f32 v[4:5], v[42:43], v[78:79], v[4:5]
	v_pk_fma_f32 v[6:7], v[46:47], v[78:79], v[6:7]
	v_add_f32_e32 v2, v4, v5
	v_add_f32_e32 v8, v6, v7
	v_pk_mul_f32 v[14:15], v[48:49], v[16:17]
	v_pk_mul_f32 v[62:63], v[50:51], v[78:79]
	v_add_f32_dpp v10, v8, v2 quad_perm:[1,0,3,2] row_mask:0xf bank_mask:0xf bound_ctrl:1
	v_pk_fma_f32 v[14:15], v[52:53], v[60:61], v[14:15] op_sel_hi:[1,0,1]
	v_pk_fma_f32 v[62:63], v[54:55], v[60:61], v[62:63] op_sel_hi:[1,0,1]
	v_add_f32_dpp v10, v10, v10 quad_perm:[2,3,0,1] row_mask:0xf bank_mask:0xf bound_ctrl:1
	ds_read_b128 v[122:125], v86 offset:26880
	ds_read_b128 v[126:129], v84 offset:26880
	v_add_f32_dpp v10, v10, v10 row_ror:4 row_mask:0xf bank_mask:0xf bound_ctrl:1
	ds_read_b128 v[130:133], v83 offset:27392
	ds_read_b128 v[134:137], v83 offset:27648
	v_add_f32_dpp v11, v10, v10 row_ror:8 row_mask:0xf bank_mask:0xf bound_ctrl:1
	ds_read_b128 v[138:141], v83 offset:27904
	ds_read_b64 v[142:143], v85 offset:28160
	v_mov_b32_dpp v12, v11 quad_perm:[0,0,2,2] row_mask:0xf bank_mask:0xf bound_ctrl:1
	v_pk_fma_f32 v[16:17], v[56:57], v[12:13], v[14:15] op_sel_hi:[1,0,1] neg_lo:[1,0,0] neg_hi:[1,0,0]
	v_pk_fma_f32 v[78:79], v[58:59], v[12:13], v[62:63] op_sel_hi:[1,0,1] neg_lo:[1,0,0] neg_hi:[1,0,0]
	v_fmac_f32_e32 v11, v60, v61
	v_cndmask_b32_e64 v87, v87, v11, s[14:15]
	s_waitcnt lgkmcnt(6)
	v_pk_mul_f32 v[4:5], v[100:101], v[16:17]
	v_pk_mul_f32 v[6:7], v[104:105], v[16:17]
	v_pk_fma_f32 v[4:5], v[102:103], v[78:79], v[4:5]
	v_pk_fma_f32 v[6:7], v[106:107], v[78:79], v[6:7]
	v_add_f32_e32 v2, v4, v5
	v_add_f32_e32 v8, v6, v7
	v_pk_mul_f32 v[14:15], v[108:109], v[16:17]
	v_pk_mul_f32 v[62:63], v[110:111], v[78:79]
	v_add_f32_dpp v10, v8, v2 quad_perm:[1,0,3,2] row_mask:0xf bank_mask:0xf bound_ctrl:1
	v_pk_fma_f32 v[14:15], v[112:113], v[120:121], v[14:15] op_sel_hi:[1,0,1]
	v_pk_fma_f32 v[62:63], v[114:115], v[120:121], v[62:63] op_sel_hi:[1,0,1]
	v_add_f32_dpp v10, v10, v10 quad_perm:[2,3,0,1] row_mask:0xf bank_mask:0xf bound_ctrl:1
	ds_read_b128 v[18:21], v86 offset:28672
	ds_read_b128 v[22:25], v84 offset:28672
	v_add_f32_dpp v10, v10, v10 row_ror:4 row_mask:0xf bank_mask:0xf bound_ctrl:1
	ds_read_b128 v[26:29], v83 offset:29184
	ds_read_b128 v[30:33], v83 offset:29440
	v_add_f32_dpp v11, v10, v10 row_ror:8 row_mask:0xf bank_mask:0xf bound_ctrl:1
	ds_read_b128 v[34:37], v83 offset:29696
	ds_read_b64 v[38:39], v85 offset:29952
	v_mov_b32_dpp v12, v11 quad_perm:[0,0,2,2] row_mask:0xf bank_mask:0xf bound_ctrl:1
	v_pk_fma_f32 v[16:17], v[116:117], v[12:13], v[14:15] op_sel_hi:[1,0,1] neg_lo:[1,0,0] neg_hi:[1,0,0]
	v_pk_fma_f32 v[78:79], v[118:119], v[12:13], v[62:63] op_sel_hi:[1,0,1] neg_lo:[1,0,0] neg_hi:[1,0,0]
	v_fmac_f32_e32 v11, v120, v121
	v_cndmask_b32_e64 v87, v87, v11, s[16:17]
	s_waitcnt lgkmcnt(6)
; #define SC_LD(S, X) do { const LAS float* q_ = sb + (S) * STEPF; X##kk = *(const LAS f32x4*)(q_ + lo_own); X##wr = *(const LAS f32x4*)(q_ + lo_oth); X##w = *(const LAS f32x4*)(q_ + 128 + 4 * cgp); \
;         X##k = *(const LAS f32x4*)(q_ + 192 + 4 * cgp); X##b = *(const LAS f32x4*)(q_ + 256 + 4 * cgp); X##vk = *(const LAS f32x2*)(q_ + 320 + 2 * row); } while (0)
; __device__ __forceinline__ void scan_phase(const Ctx& F, const float* sbg) {
;     ...
;                 SC_LD(0, A);
; #pragma unroll
;                 for (int s = 0; s < T; s += 2) { SC_LD(s + 1, B); SC_ST(s, A); if (s + 2 < T) SC_LD(s + 2, A); SC_ST(s + 1, B); }
	v_pk_mul_f32 v[4:5], v[122:123], v[16:17]
	v_pk_mul_f32 v[6:7], v[126:127], v[16:17]
	v_pk_fma_f32 v[4:5], v[124:125], v[78:79], v[4:5]
	v_pk_fma_f32 v[6:7], v[128:129], v[78:79], v[6:7]
	v_add_f32_e32 v2, v4, v5
	v_add_f32_e32 v8, v6, v7
	v_pk_mul_f32 v[14:15], v[130:131], v[16:17]
	v_pk_mul_f32 v[62:63], v[132:133], v[78:79]
	v_add_f32_dpp v10, v8, v2 quad_perm:[1,0,3,2] row_mask:0xf bank_mask:0xf bound_ctrl:1
	v_pk_fma_f32 v[14:15], v[134:135], v[142:143], v[14:15] op_sel_hi:[1,0,1]
	v_pk_fma_f32 v[62:63], v[136:137], v[142:143], v[62:63] op_sel_hi:[1,0,1]
	v_add_f32_dpp v10, v10, v10 quad_perm:[2,3,0,1] row_mask:0xf bank_mask:0xf bound_ctrl:1
	ds_read_b128 v[40:43], v86 offset:30464
	ds_read_b128 v[44:47], v84 offset:30464
	v_add_f32_dpp v10, v10, v10 row_ror:4 row_mask:0xf bank_mask:0xf bound_ctrl:1
	ds_read_b128 v[48:51], v83 offset:30976
	ds_read_b128 v[52:55], v83 offset:31232
	v_add_f32_dpp v11, v10, v10 row_ror:8 row_mask:0xf bank_mask:0xf bound_ctrl:1
	ds_read_b128 v[56:59], v83 offset:31488
	ds_read_b64 v[60:61], v85 offset:31744
	v_mov_b32_dpp v12, v11 quad_perm:[0,0,2,2] row_mask:0xf bank_mask:0xf bound_ctrl:1
	v_pk_fma_f32 v[16:17], v[138:139], v[12:13], v[14:15] op_sel_hi:[1,0,1] neg_lo:[1,0,0] neg_hi:[1,0,0]
	v_pk_fma_f32 v[78:79], v[140:141], v[12:13], v[62:63] op_sel_hi:[1,0,1] neg_lo:[1,0,0] neg_hi:[1,0,0]
	v_fmac_f32_e32 v11, v142, v143
	v_cndmask_b32_e64 v87, v87, v11, s[18:19]
	s_and_saveexec_b64 s[0:1], s[2:3]
	ds_write_b32 v94, v87 offset:512
	s_or_b64 exec, exec, s[0:1]
	s_waitcnt lgkmcnt(6)
	v_pk_mul_f32 v[4:5], v[18:19], v[16:17]
	v_pk_mul_f32 v[6:7], v[22:23], v[16:17]
	v_pk_fma_f32 v[4:5], v[20:21], v[78:79], v[4:5]
	v_pk_fma_f32 v[6:7], v[24:25], v[78:79], v[6:7]
	v_add_f32_e32 v2, v4, v5
	v_add_f32_e32 v8, v6, v7
	v_pk_mul_f32 v[14:15], v[26:27], v[16:17]
	v_pk_mul_f32 v[62:63], v[28:29], v[78:79]
	v_add_f32_dpp v10, v8, v2 quad_perm:[1,0,3,2] row_mask:0xf bank_mask:0xf bound_ctrl:1
	v_pk_fma_f32 v[14:15], v[30:31], v[38:39], v[14:15] op_sel_hi:[1,0,1]
	v_pk_fma_f32 v[62:63], v[32:33], v[38:39], v[62:63] op_sel_hi:[1,0,1]
	v_add_f32_dpp v10, v10, v10 quad_perm:[2,3,0,1] row_mask:0xf bank_mask:0xf bound_ctrl:1
	ds_read_b128 v[100:103], v86 offset:32256
	ds_read_b128 v[104:107], v84 offset:32256
	v_add_f32_dpp v10, v10, v10 row_ror:4 row_mask:0xf bank_mask:0xf bound_ctrl:1
	ds_read_b128 v[108:111], v83 offset:32768
	ds_read_b128 v[112:115], v83 offset:33024
	v_add_f32_dpp v11, v10, v10 row_ror:8 row_mask:0xf bank_mask:0xf bound_ctrl:1
	ds_read_b128 v[116:119], v83 offset:33280
	ds_read_b64 v[120:121], v85 offset:33536
	v_mov_b32_dpp v12, v11 quad_perm:[0,0,2,2] row_mask:0xf bank_mask:0xf bound_ctrl:1
	v_pk_fma_f32 v[16:17], v[34:35], v[12:13], v[14:15] op_sel_hi:[1,0,1] neg_lo:[1,0,0] neg_hi:[1,0,0]
	v_pk_fma_f32 v[78:79], v[36:37], v[12:13], v[62:63] op_sel_hi:[1,0,1] neg_lo:[1,0,0] neg_hi:[1,0,0]
	v_fmac_f32_e32 v11, v38, v39
	v_cndmask_b32_e64 v87, v87, v11, s[4:5]
	s_waitcnt lgkmcnt(6)
	v_pk_mul_f32 v[4:5], v[40:41], v[16:17]
	v_pk_mul_f32 v[6:7], v[44:45], v[16:17]
	v_pk_fma_f32 v[4:5], v[42:43], v[78:79], v[4:5]
	v_pk_fma_f32 v[6:7], v[46:47], v[78:79], v[6:7]
	v_add_f32_e32 v2, v4, v5
	v_add_f32_e32 v8, v6, v7
	v_pk_mul_f32 v[14:15], v[48:49], v[16:17]
	v_pk_mul_f32 v[62:63], v[50:51], v[78:79]
	v_add_f32_dpp v10, v8, v2 quad_perm:[1,0,3,2] row_mask:0xf bank_mask:0xf bound_ctrl:1
	v_pk_fma_f32 v[14:15], v[52:53], v[60:61], v[14:15] op_sel_hi:[1,0,1]
	v_pk_fma_f32 v[62:63], v[54:55], v[60:61], v[62:63] op_sel_hi:[1,0,1]
	v_add_f32_dpp v10, v10, v10 quad_perm:[2,3,0,1] row_mask:0xf bank_mask:0xf bound_ctrl:1
	ds_read_b128 v[122:125], v86 offset:34048
	ds_read_b128 v[126:129], v84 offset:34048
	v_add_f32_dpp v10, v10, v10 row_ror:4 row_mask:0xf bank_mask:0xf bound_ctrl:1
	ds_read_b128 v[130:133], v83 offset:34560
	ds_read_b128 v[134:137], v83 offset:34816
	v_add_f32_dpp v11, v10, v10 row_ror:8 row_mask:0xf bank_mask:0xf bound_ctrl:1
	ds_read_b128 v[138:141], v83 offset:35072
	ds_read_b64 v[142:143], v85 offset:35328
	v_mov_b32_dpp v12, v11 quad_perm:[0,0,2,2] row_mask:0xf bank_mask:0xf bound_ctrl:1
	v_pk_fma_f32 v[16:17], v[56:57], v[12:13], v[14:15] op_sel_hi:[1,0,1] neg_lo:[1,0,0] neg_hi:[1,0,0]
	v_pk_fma_f32 v[78:79], v[58:59], v[12:13], v[62:63] op_sel_hi:[1,0,1] neg_lo:[1,0,0] neg_hi:[1,0,0]
	v_fmac_f32_e32 v11, v60, v61
	v_cndmask_b32_e64 v87, v87, v11, s[6:7]
	s_waitcnt lgkmcnt(6)
	v_pk_mul_f32 v[4:5], v[100:101], v[16:17]
	v_pk_mul_f32 v[6:7], v[104:105], v[16:17]
	v_pk_fma_f32 v[4:5], v[102:103], v[78:79], v[4:5]
	v_pk_fma_f32 v[6:7], v[106:107], v[78:79], v[6:7]
	v_add_f32_e32 v2, v4, v5
	v_add_f32_e32 v8, v6, v7
	v_pk_mul_f32 v[14:15], v[108:109], v[16:17]
	v_pk_mul_f32 v[62:63], v[110:111], v[78:79]
	v_add_f32_dpp v10, v8, v2 quad_perm:[1,0,3,2] row_mask:0xf bank_mask:0xf bound_ctrl:1
	v_pk_fma_f32 v[14:15], v[112:113], v[120:121], v[14:15] op_sel_hi:[1,0,1]
	v_pk_fma_f32 v[62:63], v[114:115], v[120:121], v[62:63] op_sel_hi:[1,0,1]
	v_add_f32_dpp v10, v10, v10 quad_perm:[2,3,0,1] row_mask:0xf bank_mask:0xf bound_ctrl:1
	ds_read_b128 v[18:21], v86 offset:35840
	ds_read_b128 v[22:25], v84 offset:35840
	v_add_f32_dpp v10, v10, v10 row_ror:4 row_mask:0xf bank_mask:0xf bound_ctrl:1
	ds_read_b128 v[26:29], v83 offset:36352
	ds_read_b128 v[30:33], v83 offset:36608
	v_add_f32_dpp v11, v10, v10 row_ror:8 row_mask:0xf bank_mask:0xf bound_ctrl:1
	ds_read_b128 v[34:37], v83 offset:36864
	ds_read_b64 v[38:39], v85 offset:37120
	v_mov_b32_dpp v12, v11 quad_perm:[0,0,2,2] row_mask:0xf bank_mask:0xf bound_ctrl:1
	v_pk_fma_f32 v[16:17], v[116:117], v[12:13], v[14:15] op_sel_hi:[1,0,1] neg_lo:[1,0,0] neg_hi:[1,0,0]
	v_pk_fma_f32 v[78:79], v[118:119], v[12:13], v[62:63] op_sel_hi:[1,0,1] neg_lo:[1,0,0] neg_hi:[1,0,0]
	v_fmac_f32_e32 v11, v120, v121
	v_cndmask_b32_e64 v87, v87, v11, s[8:9]
	s_waitcnt lgkmcnt(6)
; #define SC_LD(S, X) do { const LAS float* q_ = sb + (S) * STEPF; X##kk = *(const LAS f32x4*)(q_ + lo_own); X##wr = *(const LAS f32x4*)(q_ + lo_oth); X##w = *(const LAS f32x4*)(q_ + 128 + 4 * cgp); \
;         X##k = *(const LAS f32x4*)(q_ + 192 + 4 * cgp); X##b = *(const LAS f32x4*)(q_ + 256 + 4 * cgp); X##vk = *(const LAS f32x2*)(q_ + 320 + 2 * row); } while (0)
; __device__ __forceinline__ void scan_phase(const Ctx& F, const float* sbg) {
;     ...
;                 SC_LD(0, A);
; #pragma unroll
;                 for (int s = 0; s < T; s += 2) { SC_LD(s + 1, B); SC_ST(s, A); if (s + 2 < T) SC_LD(s + 2, A); SC_ST(s + 1, B); }
	v_pk_mul_f32 v[4:5], v[122:123], v[16:17]
	v_pk_mul_f32 v[6:7], v[126:127], v[16:17]
	v_pk_fma_f32 v[4:5], v[124:125], v[78:79], v[4:5]
	v_pk_fma_f32 v[6:7], v[128:129], v[78:79], v[6:7]
	v_add_f32_e32 v2, v4, v5
	v_add_f32_e32 v8, v6, v7
	v_pk_mul_f32 v[14:15], v[130:131], v[16:17]
	v_pk_mul_f32 v[62:63], v[132:133], v[78:79]
	v_add_f32_dpp v10, v8, v2 quad_perm:[1,0,3,2] row_mask:0xf bank_mask:0xf bound_ctrl:1
	v_pk_fma_f32 v[14:15], v[134:135], v[142:143], v[14:15] op_sel_hi:[1,0,1]
	v_pk_fma_f32 v[62:63], v[136:137], v[142:143], v[62:63] op_sel_hi:[1,0,1]
	v_add_f32_dpp v10, v10, v10 quad_perm:[2,3,0,1] row_mask:0xf bank_mask:0xf bound_ctrl:1
	ds_read_b128 v[40:43], v86 offset:37632
	ds_read_b128 v[44:47], v84 offset:37632
	v_add_f32_dpp v10, v10, v10 row_ror:4 row_mask:0xf bank_mask:0xf bound_ctrl:1
	ds_read_b128 v[48:51], v83 offset:38144
	ds_read_b128 v[52:55], v83 offset:38400
	v_add_f32_dpp v11, v10, v10 row_ror:8 row_mask:0xf bank_mask:0xf bound_ctrl:1
	ds_read_b128 v[56:59], v83 offset:38656
	ds_read_b64 v[60:61], v85 offset:38912
	v_mov_b32_dpp v12, v11 quad_perm:[0,0,2,2] row_mask:0xf bank_mask:0xf bound_ctrl:1
	v_pk_fma_f32 v[16:17], v[138:139], v[12:13], v[14:15] op_sel_hi:[1,0,1] neg_lo:[1,0,0] neg_hi:[1,0,0]
	v_pk_fma_f32 v[78:79], v[140:141], v[12:13], v[62:63] op_sel_hi:[1,0,1] neg_lo:[1,0,0] neg_hi:[1,0,0]
	v_fmac_f32_e32 v11, v142, v143
	v_cndmask_b32_e64 v87, v87, v11, s[10:11]
	s_waitcnt lgkmcnt(6)
	v_pk_mul_f32 v[4:5], v[18:19], v[16:17]
	v_pk_mul_f32 v[6:7], v[22:23], v[16:17]
	v_pk_fma_f32 v[4:5], v[20:21], v[78:79], v[4:5]
	v_pk_fma_f32 v[6:7], v[24:25], v[78:79], v[6:7]
	v_add_f32_e32 v2, v4, v5
	v_add_f32_e32 v8, v6, v7
	v_pk_mul_f32 v[14:15], v[26:27], v[16:17]
	v_pk_mul_f32 v[62:63], v[28:29], v[78:79]
	v_add_f32_dpp v10, v8, v2 quad_perm:[1,0,3,2] row_mask:0xf bank_mask:0xf bound_ctrl:1
	v_pk_fma_f32 v[14:15], v[30:31], v[38:39], v[14:15] op_sel_hi:[1,0,1]
	v_pk_fma_f32 v[62:63], v[32:33], v[38:39], v[62:63] op_sel_hi:[1,0,1]
	v_add_f32_dpp v10, v10, v10 quad_perm:[2,3,0,1] row_mask:0xf bank_mask:0xf bound_ctrl:1
	ds_read_b128 v[100:103], v86 offset:39424
	ds_read_b128 v[104:107], v84 offset:39424
	v_add_f32_dpp v10, v10, v10 row_ror:4 row_mask:0xf bank_mask:0xf bound_ctrl:1
	ds_read_b128 v[108:111], v83 offset:39936
	ds_read_b128 v[112:115], v83 offset:40192
	v_add_f32_dpp v11, v10, v10 row_ror:8 row_mask:0xf bank_mask:0xf bound_ctrl:1
	ds_read_b128 v[116:119], v83 offset:40448
	ds_read_b64 v[120:121], v85 offset:40704
	v_mov_b32_dpp v12, v11 quad_perm:[0,0,2,2] row_mask:0xf bank_mask:0xf bound_ctrl:1
	v_pk_fma_f32 v[16:17], v[34:35], v[12:13], v[14:15] op_sel_hi:[1,0,1] neg_lo:[1,0,0] neg_hi:[1,0,0]
	v_pk_fma_f32 v[78:79], v[36:37], v[12:13], v[62:63] op_sel_hi:[1,0,1] neg_lo:[1,0,0] neg_hi:[1,0,0]
	v_fmac_f32_e32 v11, v38, v39
	v_cndmask_b32_e64 v87, v87, v11, s[12:13]
	s_waitcnt lgkmcnt(6)
	v_pk_mul_f32 v[4:5], v[40:41], v[16:17]
	v_pk_mul_f32 v[6:7], v[44:45], v[16:17]
	v_pk_fma_f32 v[4:5], v[42:43], v[78:79], v[4:5]
	v_pk_fma_f32 v[6:7], v[46:47], v[78:79], v[6:7]
	v_add_f32_e32 v2, v4, v5
	v_add_f32_e32 v8, v6, v7
	v_pk_mul_f32 v[14:15], v[48:49], v[16:17]
	v_pk_mul_f32 v[62:63], v[50:51], v[78:79]
	v_add_f32_dpp v10, v8, v2 quad_perm:[1,0,3,2] row_mask:0xf bank_mask:0xf bound_ctrl:1
	v_pk_fma_f32 v[14:15], v[52:53], v[60:61], v[14:15] op_sel_hi:[1,0,1]
	v_pk_fma_f32 v[62:63], v[54:55], v[60:61], v[62:63] op_sel_hi:[1,0,1]
	v_add_f32_dpp v10, v10, v10 quad_perm:[2,3,0,1] row_mask:0xf bank_mask:0xf bound_ctrl:1
	ds_read_b128 v[122:125], v86 offset:41216
	ds_read_b128 v[126:129], v84 offset:41216
	v_add_f32_dpp v10, v10, v10 row_ror:4 row_mask:0xf bank_mask:0xf bound_ctrl:1
	ds_read_b128 v[130:133], v83 offset:41728
	ds_read_b128 v[134:137], v83 offset:41984
	v_add_f32_dpp v11, v10, v10 row_ror:8 row_mask:0xf bank_mask:0xf bound_ctrl:1
	ds_read_b128 v[138:141], v83 offset:42240
	ds_read_b64 v[142:143], v85 offset:42496
	v_mov_b32_dpp v12, v11 quad_perm:[0,0,2,2] row_mask:0xf bank_mask:0xf bound_ctrl:1
	v_pk_fma_f32 v[16:17], v[56:57], v[12:13], v[14:15] op_sel_hi:[1,0,1] neg_lo:[1,0,0] neg_hi:[1,0,0]
	v_pk_fma_f32 v[78:79], v[58:59], v[12:13], v[62:63] op_sel_hi:[1,0,1] neg_lo:[1,0,0] neg_hi:[1,0,0]
	v_fmac_f32_e32 v11, v60, v61
	v_cndmask_b32_e64 v87, v87, v11, s[14:15]
	s_waitcnt lgkmcnt(6)
	v_pk_mul_f32 v[4:5], v[100:101], v[16:17]
	v_pk_mul_f32 v[6:7], v[104:105], v[16:17]
	v_pk_fma_f32 v[4:5], v[102:103], v[78:79], v[4:5]
	v_pk_fma_f32 v[6:7], v[106:107], v[78:79], v[6:7]
	v_add_f32_e32 v2, v4, v5
	v_add_f32_e32 v8, v6, v7
	v_pk_mul_f32 v[14:15], v[108:109], v[16:17]
	v_pk_mul_f32 v[62:63], v[110:111], v[78:79]
	v_add_f32_dpp v10, v8, v2 quad_perm:[1,0,3,2] row_mask:0xf bank_mask:0xf bound_ctrl:1
	v_pk_fma_f32 v[14:15], v[112:113], v[120:121], v[14:15] op_sel_hi:[1,0,1]
	v_pk_fma_f32 v[62:63], v[114:115], v[120:121], v[62:63] op_sel_hi:[1,0,1]
	v_add_f32_dpp v10, v10, v10 quad_perm:[2,3,0,1] row_mask:0xf bank_mask:0xf bound_ctrl:1
	ds_read_b128 v[18:21], v86 offset:43008
	ds_read_b128 v[22:25], v84 offset:43008
	v_add_f32_dpp v10, v10, v10 row_ror:4 row_mask:0xf bank_mask:0xf bound_ctrl:1
	ds_read_b128 v[26:29], v83 offset:43520
	ds_read_b128 v[30:33], v83 offset:43776
	v_add_f32_dpp v11, v10, v10 row_ror:8 row_mask:0xf bank_mask:0xf bound_ctrl:1
	ds_read_b128 v[34:37], v83 offset:44032
	ds_read_b64 v[38:39], v85 offset:44288
	v_mov_b32_dpp v12, v11 quad_perm:[0,0,2,2] row_mask:0xf bank_mask:0xf bound_ctrl:1
	v_pk_fma_f32 v[16:17], v[116:117], v[12:13], v[14:15] op_sel_hi:[1,0,1] neg_lo:[1,0,0] neg_hi:[1,0,0]
	v_pk_fma_f32 v[78:79], v[118:119], v[12:13], v[62:63] op_sel_hi:[1,0,1] neg_lo:[1,0,0] neg_hi:[1,0,0]
	v_fmac_f32_e32 v11, v120, v121
	v_cndmask_b32_e64 v87, v87, v11, s[16:17]
	s_waitcnt lgkmcnt(6)
; #define SC_LD(S, X) do { const LAS float* q_ = sb + (S) * STEPF; X##kk = *(const LAS f32x4*)(q_ + lo_own); X##wr = *(const LAS f32x4*)(q_ + lo_oth); X##w = *(const LAS f32x4*)(q_ + 128 + 4 * cgp); \
;         X##k = *(const LAS f32x4*)(q_ + 192 + 4 * cgp); X##b = *(const LAS f32x4*)(q_ + 256 + 4 * cgp); X##vk = *(const LAS f32x2*)(q_ + 320 + 2 * row); } while (0)
; __device__ __forceinline__ void scan_phase(const Ctx& F, const float* sbg) {
;     ...
;                 SC_LD(0, A);
; #pragma unroll
;                 for (int s = 0; s < T; s += 2) { SC_LD(s + 1, B); SC_ST(s, A); if (s + 2 < T) SC_LD(s + 2, A); SC_ST(s + 1, B); }
	v_pk_mul_f32 v[4:5], v[122:123], v[16:17]
	v_pk_mul_f32 v[6:7], v[126:127], v[16:17]
	v_pk_fma_f32 v[4:5], v[124:125], v[78:79], v[4:5]
	v_pk_fma_f32 v[6:7], v[128:129], v[78:79], v[6:7]
	v_add_f32_e32 v2, v4, v5
	v_add_f32_e32 v8, v6, v7
	v_pk_mul_f32 v[14:15], v[130:131], v[16:17]
	v_pk_mul_f32 v[62:63], v[132:133], v[78:79]
	v_add_f32_dpp v10, v8, v2 quad_perm:[1,0,3,2] row_mask:0xf bank_mask:0xf bound_ctrl:1
	v_pk_fma_f32 v[14:15], v[134:135], v[142:143], v[14:15] op_sel_hi:[1,0,1]
	v_pk_fma_f32 v[62:63], v[136:137], v[142:143], v[62:63] op_sel_hi:[1,0,1]
	v_add_f32_dpp v10, v10, v10 quad_perm:[2,3,0,1] row_mask:0xf bank_mask:0xf bound_ctrl:1
	ds_read_b128 v[40:43], v86 offset:44800
	ds_read_b128 v[44:47], v84 offset:44800
	v_add_f32_dpp v10, v10, v10 row_ror:4 row_mask:0xf bank_mask:0xf bound_ctrl:1
	ds_read_b128 v[48:51], v83 offset:45312
	ds_read_b128 v[52:55], v83 offset:45568
	v_add_f32_dpp v11, v10, v10 row_ror:8 row_mask:0xf bank_mask:0xf bound_ctrl:1
	ds_read_b128 v[56:59], v83 offset:45824
	ds_read_b64 v[60:61], v85 offset:46080
	v_mov_b32_dpp v12, v11 quad_perm:[0,0,2,2] row_mask:0xf bank_mask:0xf bound_ctrl:1
	v_pk_fma_f32 v[16:17], v[138:139], v[12:13], v[14:15] op_sel_hi:[1,0,1] neg_lo:[1,0,0] neg_hi:[1,0,0]
	v_pk_fma_f32 v[78:79], v[140:141], v[12:13], v[62:63] op_sel_hi:[1,0,1] neg_lo:[1,0,0] neg_hi:[1,0,0]
	v_fmac_f32_e32 v11, v142, v143
	v_cndmask_b32_e64 v87, v87, v11, s[18:19]
	s_and_saveexec_b64 s[0:1], s[2:3]
	ds_write_b32 v94, v87 offset:1024
	s_or_b64 exec, exec, s[0:1]
	s_waitcnt lgkmcnt(6)
	v_pk_mul_f32 v[4:5], v[18:19], v[16:17]
	v_pk_mul_f32 v[6:7], v[22:23], v[16:17]
	v_pk_fma_f32 v[4:5], v[20:21], v[78:79], v[4:5]
	v_pk_fma_f32 v[6:7], v[24:25], v[78:79], v[6:7]
	v_add_f32_e32 v2, v4, v5
	v_add_f32_e32 v8, v6, v7
	v_pk_mul_f32 v[14:15], v[26:27], v[16:17]
	v_pk_mul_f32 v[62:63], v[28:29], v[78:79]
	v_add_f32_dpp v10, v8, v2 quad_perm:[1,0,3,2] row_mask:0xf bank_mask:0xf bound_ctrl:1
	v_pk_fma_f32 v[14:15], v[30:31], v[38:39], v[14:15] op_sel_hi:[1,0,1]
	v_pk_fma_f32 v[62:63], v[32:33], v[38:39], v[62:63] op_sel_hi:[1,0,1]
	v_add_f32_dpp v10, v10, v10 quad_perm:[2,3,0,1] row_mask:0xf bank_mask:0xf bound_ctrl:1
	ds_read_b128 v[100:103], v86 offset:46592
	ds_read_b128 v[104:107], v84 offset:46592
	v_add_f32_dpp v10, v10, v10 row_ror:4 row_mask:0xf bank_mask:0xf bound_ctrl:1
	ds_read_b128 v[108:111], v83 offset:47104
	ds_read_b128 v[112:115], v83 offset:47360
	v_add_f32_dpp v11, v10, v10 row_ror:8 row_mask:0xf bank_mask:0xf bound_ctrl:1
	ds_read_b128 v[116:119], v83 offset:47616
	ds_read_b64 v[120:121], v85 offset:47872
	v_mov_b32_dpp v12, v11 quad_perm:[0,0,2,2] row_mask:0xf bank_mask:0xf bound_ctrl:1
	v_pk_fma_f32 v[16:17], v[34:35], v[12:13], v[14:15] op_sel_hi:[1,0,1] neg_lo:[1,0,0] neg_hi:[1,0,0]
	v_pk_fma_f32 v[78:79], v[36:37], v[12:13], v[62:63] op_sel_hi:[1,0,1] neg_lo:[1,0,0] neg_hi:[1,0,0]
	v_fmac_f32_e32 v11, v38, v39
	v_cndmask_b32_e64 v87, v87, v11, s[4:5]
	s_waitcnt lgkmcnt(6)
	v_pk_mul_f32 v[4:5], v[40:41], v[16:17]
	v_pk_mul_f32 v[6:7], v[44:45], v[16:17]
	v_pk_fma_f32 v[4:5], v[42:43], v[78:79], v[4:5]
	v_pk_fma_f32 v[6:7], v[46:47], v[78:79], v[6:7]
	v_add_f32_e32 v2, v4, v5
	v_add_f32_e32 v8, v6, v7
	v_pk_mul_f32 v[14:15], v[48:49], v[16:17]
	v_pk_mul_f32 v[62:63], v[50:51], v[78:79]
	v_add_f32_dpp v10, v8, v2 quad_perm:[1,0,3,2] row_mask:0xf bank_mask:0xf bound_ctrl:1
	v_pk_fma_f32 v[14:15], v[52:53], v[60:61], v[14:15] op_sel_hi:[1,0,1]
	v_pk_fma_f32 v[62:63], v[54:55], v[60:61], v[62:63] op_sel_hi:[1,0,1]
	v_add_f32_dpp v10, v10, v10 quad_perm:[2,3,0,1] row_mask:0xf bank_mask:0xf bound_ctrl:1
	ds_read_b128 v[122:125], v86 offset:48384
	ds_read_b128 v[126:129], v84 offset:48384
	v_add_f32_dpp v10, v10, v10 row_ror:4 row_mask:0xf bank_mask:0xf bound_ctrl:1
	ds_read_b128 v[130:133], v83 offset:48896
	ds_read_b128 v[134:137], v83 offset:49152
	v_add_f32_dpp v11, v10, v10 row_ror:8 row_mask:0xf bank_mask:0xf bound_ctrl:1
	ds_read_b128 v[138:141], v83 offset:49408
	ds_read_b64 v[142:143], v85 offset:49664
	v_mov_b32_dpp v12, v11 quad_perm:[0,0,2,2] row_mask:0xf bank_mask:0xf bound_ctrl:1
	v_pk_fma_f32 v[16:17], v[56:57], v[12:13], v[14:15] op_sel_hi:[1,0,1] neg_lo:[1,0,0] neg_hi:[1,0,0]
	v_pk_fma_f32 v[78:79], v[58:59], v[12:13], v[62:63] op_sel_hi:[1,0,1] neg_lo:[1,0,0] neg_hi:[1,0,0]
	v_fmac_f32_e32 v11, v60, v61
	v_cndmask_b32_e64 v87, v87, v11, s[6:7]
	s_waitcnt lgkmcnt(6)
	v_pk_mul_f32 v[4:5], v[100:101], v[16:17]
	v_pk_mul_f32 v[6:7], v[104:105], v[16:17]
	v_pk_fma_f32 v[4:5], v[102:103], v[78:79], v[4:5]
	v_pk_fma_f32 v[6:7], v[106:107], v[78:79], v[6:7]
	v_add_f32_e32 v2, v4, v5
	v_add_f32_e32 v8, v6, v7
	v_pk_mul_f32 v[14:15], v[108:109], v[16:17]
	v_pk_mul_f32 v[62:63], v[110:111], v[78:79]
	v_add_f32_dpp v10, v8, v2 quad_perm:[1,0,3,2] row_mask:0xf bank_mask:0xf bound_ctrl:1
	v_pk_fma_f32 v[14:15], v[112:113], v[120:121], v[14:15] op_sel_hi:[1,0,1]
	v_pk_fma_f32 v[62:63], v[114:115], v[120:121], v[62:63] op_sel_hi:[1,0,1]
	v_add_f32_dpp v10, v10, v10 quad_perm:[2,3,0,1] row_mask:0xf bank_mask:0xf bound_ctrl:1
	ds_read_b128 v[18:21], v86 offset:50176
	ds_read_b128 v[22:25], v84 offset:50176
	v_add_f32_dpp v10, v10, v10 row_ror:4 row_mask:0xf bank_mask:0xf bound_ctrl:1
	ds_read_b128 v[26:29], v83 offset:50688
	ds_read_b128 v[30:33], v83 offset:50944
	v_add_f32_dpp v11, v10, v10 row_ror:8 row_mask:0xf bank_mask:0xf bound_ctrl:1
	ds_read_b128 v[34:37], v83 offset:51200
	ds_read_b64 v[38:39], v85 offset:51456
	v_mov_b32_dpp v12, v11 quad_perm:[0,0,2,2] row_mask:0xf bank_mask:0xf bound_ctrl:1
	v_pk_fma_f32 v[16:17], v[116:117], v[12:13], v[14:15] op_sel_hi:[1,0,1] neg_lo:[1,0,0] neg_hi:[1,0,0]
	v_pk_fma_f32 v[78:79], v[118:119], v[12:13], v[62:63] op_sel_hi:[1,0,1] neg_lo:[1,0,0] neg_hi:[1,0,0]
	v_fmac_f32_e32 v11, v120, v121
	v_cndmask_b32_e64 v87, v87, v11, s[8:9]
	s_waitcnt lgkmcnt(6)
; #define LAS __attribute__((address_space(3)))
; #define SC_LD(S, X) do { const LAS float* q_ = sb + (S) * STEPF; X##kk = *(const LAS f32x4*)(q_ + lo_own); X##wr = *(const LAS f32x4*)(q_ + lo_oth); X##w = *(const LAS f32x4*)(q_ + 128 + 4 * cgp); \
;         X##k = *(const LAS f32x4*)(q_ + 192 + 4 * cgp); X##b = *(const LAS f32x4*)(q_ + 256 + 4 * cgp); X##vk = *(const LAS f32x2*)(q_ + 320 + 2 * row); } while (0)
; __device__ __forceinline__ void scan_phase(const Ctx& F, const float* sbg) {
;     ...
;             for (int ch = 0; ch < NCH; ++ch) {
;                 const LAS float* sb = bufs + (ch & 1) * (T * STEPF); LAS float* yb = ybufs + (ch & 1) * (T * 16) + rl;
;                 f32x4 Akk, Awr, Aw, Ak, Ab, Bkk, Bwr, Bw, Bk, Bb; f32x2 Avk, Bvk;
;     ...
;                 SC_LD(0, A);
; #pragma unroll
;                 for (int s = 0; s < T; s += 2) { SC_LD(s + 1, B); SC_ST(s, A); if (s + 2 < T) SC_LD(s + 2, A); SC_ST(s + 1, B); }
;     ...
;                 asm volatile("s_waitcnt lgkmcnt(0)\n\ts_barrier" ::: "memory");
	v_pk_mul_f32 v[4:5], v[122:123], v[16:17]
	v_pk_mul_f32 v[6:7], v[126:127], v[16:17]
	v_pk_fma_f32 v[4:5], v[124:125], v[78:79], v[4:5]
	v_pk_fma_f32 v[6:7], v[128:129], v[78:79], v[6:7]
	v_add_f32_e32 v2, v4, v5
	v_add_f32_e32 v8, v6, v7
	v_pk_mul_f32 v[14:15], v[130:131], v[16:17]
	v_pk_mul_f32 v[62:63], v[132:133], v[78:79]
	v_add_f32_dpp v10, v8, v2 quad_perm:[1,0,3,2] row_mask:0xf bank_mask:0xf bound_ctrl:1
	v_pk_fma_f32 v[14:15], v[134:135], v[142:143], v[14:15] op_sel_hi:[1,0,1]
	v_pk_fma_f32 v[62:63], v[136:137], v[142:143], v[62:63] op_sel_hi:[1,0,1]
	v_add_f32_dpp v10, v10, v10 quad_perm:[2,3,0,1] row_mask:0xf bank_mask:0xf bound_ctrl:1
	ds_read_b128 v[40:43], v86 offset:51968
	ds_read_b128 v[44:47], v84 offset:51968
	v_add_f32_dpp v10, v10, v10 row_ror:4 row_mask:0xf bank_mask:0xf bound_ctrl:1
	ds_read_b128 v[48:51], v83 offset:52480
	ds_read_b128 v[52:55], v83 offset:52736
	v_add_f32_dpp v11, v10, v10 row_ror:8 row_mask:0xf bank_mask:0xf bound_ctrl:1
	ds_read_b128 v[56:59], v83 offset:52992
	ds_read_b64 v[60:61], v85 offset:53248
	v_mov_b32_dpp v12, v11 quad_perm:[0,0,2,2] row_mask:0xf bank_mask:0xf bound_ctrl:1
	v_pk_fma_f32 v[16:17], v[138:139], v[12:13], v[14:15] op_sel_hi:[1,0,1] neg_lo:[1,0,0] neg_hi:[1,0,0]
	v_pk_fma_f32 v[78:79], v[140:141], v[12:13], v[62:63] op_sel_hi:[1,0,1] neg_lo:[1,0,0] neg_hi:[1,0,0]
	v_fmac_f32_e32 v11, v142, v143
	v_cndmask_b32_e64 v87, v87, v11, s[10:11]
	s_waitcnt lgkmcnt(6)
	v_pk_mul_f32 v[4:5], v[18:19], v[16:17]
	v_pk_mul_f32 v[6:7], v[22:23], v[16:17]
	v_pk_fma_f32 v[4:5], v[20:21], v[78:79], v[4:5]
	v_pk_fma_f32 v[6:7], v[24:25], v[78:79], v[6:7]
	v_add_f32_e32 v2, v4, v5
	v_add_f32_e32 v8, v6, v7
	v_pk_mul_f32 v[14:15], v[26:27], v[16:17]
	v_pk_mul_f32 v[62:63], v[28:29], v[78:79]
	v_add_f32_dpp v10, v8, v2 quad_perm:[1,0,3,2] row_mask:0xf bank_mask:0xf bound_ctrl:1
	v_pk_fma_f32 v[14:15], v[30:31], v[38:39], v[14:15] op_sel_hi:[1,0,1]
	v_pk_fma_f32 v[62:63], v[32:33], v[38:39], v[62:63] op_sel_hi:[1,0,1]
	v_add_f32_dpp v10, v10, v10 quad_perm:[2,3,0,1] row_mask:0xf bank_mask:0xf bound_ctrl:1
	ds_read_b128 v[100:103], v86 offset:53760
	ds_read_b128 v[104:107], v84 offset:53760
	v_add_f32_dpp v10, v10, v10 row_ror:4 row_mask:0xf bank_mask:0xf bound_ctrl:1
	ds_read_b128 v[108:111], v83 offset:54272
	ds_read_b128 v[112:115], v83 offset:54528
	v_add_f32_dpp v11, v10, v10 row_ror:8 row_mask:0xf bank_mask:0xf bound_ctrl:1
	ds_read_b128 v[116:119], v83 offset:54784
	ds_read_b64 v[120:121], v85 offset:55040
	v_mov_b32_dpp v12, v11 quad_perm:[0,0,2,2] row_mask:0xf bank_mask:0xf bound_ctrl:1
	v_pk_fma_f32 v[16:17], v[34:35], v[12:13], v[14:15] op_sel_hi:[1,0,1] neg_lo:[1,0,0] neg_hi:[1,0,0]
	v_pk_fma_f32 v[78:79], v[36:37], v[12:13], v[62:63] op_sel_hi:[1,0,1] neg_lo:[1,0,0] neg_hi:[1,0,0]
	v_fmac_f32_e32 v11, v38, v39
	v_cndmask_b32_e64 v87, v87, v11, s[12:13]
	s_waitcnt lgkmcnt(6)
	v_pk_mul_f32 v[4:5], v[40:41], v[16:17]
	v_pk_mul_f32 v[6:7], v[44:45], v[16:17]
	v_pk_fma_f32 v[4:5], v[42:43], v[78:79], v[4:5]
	v_pk_fma_f32 v[6:7], v[46:47], v[78:79], v[6:7]
	v_add_f32_e32 v2, v4, v5
	v_add_f32_e32 v8, v6, v7
	v_pk_mul_f32 v[14:15], v[48:49], v[16:17]
	v_pk_mul_f32 v[62:63], v[50:51], v[78:79]
	v_add_f32_dpp v10, v8, v2 quad_perm:[1,0,3,2] row_mask:0xf bank_mask:0xf bound_ctrl:1
	v_pk_fma_f32 v[14:15], v[52:53], v[60:61], v[14:15] op_sel_hi:[1,0,1]
	v_pk_fma_f32 v[62:63], v[54:55], v[60:61], v[62:63] op_sel_hi:[1,0,1]
	v_add_f32_dpp v10, v10, v10 quad_perm:[2,3,0,1] row_mask:0xf bank_mask:0xf bound_ctrl:1
	ds_read_b128 v[122:125], v86 offset:55552
	ds_read_b128 v[126:129], v84 offset:55552
	v_add_f32_dpp v10, v10, v10 row_ror:4 row_mask:0xf bank_mask:0xf bound_ctrl:1
	ds_read_b128 v[130:133], v83 offset:56064
	ds_read_b128 v[134:137], v83 offset:56320
	v_add_f32_dpp v11, v10, v10 row_ror:8 row_mask:0xf bank_mask:0xf bound_ctrl:1
	ds_read_b128 v[138:141], v83 offset:56576
	ds_read_b64 v[142:143], v85 offset:56832
	v_mov_b32_dpp v12, v11 quad_perm:[0,0,2,2] row_mask:0xf bank_mask:0xf bound_ctrl:1
	v_pk_fma_f32 v[16:17], v[56:57], v[12:13], v[14:15] op_sel_hi:[1,0,1] neg_lo:[1,0,0] neg_hi:[1,0,0]
	v_pk_fma_f32 v[78:79], v[58:59], v[12:13], v[62:63] op_sel_hi:[1,0,1] neg_lo:[1,0,0] neg_hi:[1,0,0]
	v_fmac_f32_e32 v11, v60, v61
	v_cndmask_b32_e64 v87, v87, v11, s[14:15]
	s_waitcnt lgkmcnt(6)
	v_pk_mul_f32 v[4:5], v[100:101], v[16:17]
	v_pk_mul_f32 v[6:7], v[104:105], v[16:17]
	v_pk_fma_f32 v[4:5], v[102:103], v[78:79], v[4:5]
	v_pk_fma_f32 v[6:7], v[106:107], v[78:79], v[6:7]
	v_add_f32_e32 v2, v4, v5
	v_add_f32_e32 v8, v6, v7
	v_pk_mul_f32 v[14:15], v[108:109], v[16:17]
	v_pk_mul_f32 v[62:63], v[110:111], v[78:79]
	v_add_f32_dpp v10, v8, v2 quad_perm:[1,0,3,2] row_mask:0xf bank_mask:0xf bound_ctrl:1
	v_pk_fma_f32 v[14:15], v[112:113], v[120:121], v[14:15] op_sel_hi:[1,0,1]
	v_pk_fma_f32 v[62:63], v[114:115], v[120:121], v[62:63] op_sel_hi:[1,0,1]
	v_add_f32_dpp v10, v10, v10 quad_perm:[2,3,0,1] row_mask:0xf bank_mask:0xf bound_ctrl:1
	s_nop 1
	v_add_f32_dpp v10, v10, v10 row_ror:4 row_mask:0xf bank_mask:0xf bound_ctrl:1
	s_nop 1
	v_add_f32_dpp v11, v10, v10 row_ror:8 row_mask:0xf bank_mask:0xf bound_ctrl:1
	s_nop 1
	v_mov_b32_dpp v12, v11 quad_perm:[0,0,2,2] row_mask:0xf bank_mask:0xf bound_ctrl:1
	v_pk_fma_f32 v[16:17], v[116:117], v[12:13], v[14:15] op_sel_hi:[1,0,1] neg_lo:[1,0,0] neg_hi:[1,0,0]
	v_pk_fma_f32 v[78:79], v[118:119], v[12:13], v[62:63] op_sel_hi:[1,0,1] neg_lo:[1,0,0] neg_hi:[1,0,0]
	v_fmac_f32_e32 v11, v120, v121
	v_cndmask_b32_e64 v87, v87, v11, s[16:17]
	s_waitcnt lgkmcnt(0)
	v_pk_mul_f32 v[4:5], v[122:123], v[16:17]
	v_pk_mul_f32 v[6:7], v[126:127], v[16:17]
	v_pk_fma_f32 v[4:5], v[124:125], v[78:79], v[4:5]
	v_pk_fma_f32 v[6:7], v[128:129], v[78:79], v[6:7]
	v_add_f32_e32 v2, v4, v5
	v_add_f32_e32 v8, v6, v7
	v_pk_mul_f32 v[14:15], v[130:131], v[16:17]
	v_pk_mul_f32 v[62:63], v[132:133], v[78:79]
	v_add_f32_dpp v10, v8, v2 quad_perm:[1,0,3,2] row_mask:0xf bank_mask:0xf bound_ctrl:1
	v_pk_fma_f32 v[14:15], v[134:135], v[142:143], v[14:15] op_sel_hi:[1,0,1]
	v_pk_fma_f32 v[62:63], v[136:137], v[142:143], v[62:63] op_sel_hi:[1,0,1]
	v_add_f32_dpp v10, v10, v10 quad_perm:[2,3,0,1] row_mask:0xf bank_mask:0xf bound_ctrl:1
	s_nop 1
	v_add_f32_dpp v10, v10, v10 row_ror:4 row_mask:0xf bank_mask:0xf bound_ctrl:1
	s_nop 1
	v_add_f32_dpp v11, v10, v10 row_ror:8 row_mask:0xf bank_mask:0xf bound_ctrl:1
	s_nop 1
	v_mov_b32_dpp v12, v11 quad_perm:[0,0,2,2] row_mask:0xf bank_mask:0xf bound_ctrl:1
	v_pk_fma_f32 v[16:17], v[138:139], v[12:13], v[14:15] op_sel_hi:[1,0,1] neg_lo:[1,0,0] neg_hi:[1,0,0]
	v_pk_fma_f32 v[78:79], v[140:141], v[12:13], v[62:63] op_sel_hi:[1,0,1] neg_lo:[1,0,0] neg_hi:[1,0,0]
	v_fmac_f32_e32 v11, v142, v143
	v_cndmask_b32_e64 v87, v87, v11, s[18:19]
	s_and_saveexec_b64 s[0:1], s[2:3]
	ds_write_b32 v94, v87 offset:1536
	s_or_b64 exec, exec, s[0:1]
	s_waitcnt lgkmcnt(0)
	s_barrier
	s_add_i32 s22, s22, 1
	s_cmpk_eq_i32 s22, 0x80
	s_cbranch_scc0 .Lscan_chunk
	s_branch .LBB0_660
